# v37 + code placement: hot loop heads padded so that in every GEMM K loop the MFMAs start at 4 mod 8 bytes (the placement the best versions happened to have in the big loops)
# baseline (speedup 1.0000x reference)
.LBB0_732:
	v_sub_f32_e32 v65, v65, v216
	v_sub_f32_e32 v64, v64, v216
	v_sub_f32_e32 v63, v63, v216
	v_sub_f32_e32 v62, v62, v216
	v_sub_f32_e32 v61, v61, v216
	v_sub_f32_e32 v60, v60, v216
	v_sub_f32_e32 v59, v59, v216
	v_sub_f32_e32 v58, v58, v216
	v_sub_f32_e32 v57, v57, v216
	v_sub_f32_e32 v56, v56, v216
	v_sub_f32_e32 v55, v55, v216
	v_sub_f32_e32 v54, v54, v216
	v_sub_f32_e32 v53, v53, v216
	v_sub_f32_e32 v52, v52, v216
	v_sub_f32_e32 v51, v51, v216
	v_sub_f32_e32 v50, v50, v216
	v_sub_f32_e32 v49, v49, v216
	v_sub_f32_e32 v48, v48, v216
	v_sub_f32_e32 v47, v47, v216
	v_sub_f32_e32 v46, v46, v216
	v_sub_f32_e32 v45, v45, v216
	v_sub_f32_e32 v44, v44, v216
	v_sub_f32_e32 v43, v43, v216
	v_sub_f32_e32 v42, v42, v216
	v_sub_f32_e32 v41, v41, v216
	v_sub_f32_e32 v40, v40, v216
	v_sub_f32_e32 v39, v39, v216
	v_sub_f32_e32 v38, v38, v216
	v_sub_f32_e32 v37, v37, v216
	v_sub_f32_e32 v36, v36, v216
	v_sub_f32_e32 v35, v35, v216
	v_sub_f32_e32 v34, v34, v216
	s_nop 0
